# v16: compress-GEMM2 tile moved from head of phase 4 to tail of phase 2 (CMP1 blocks publish+wait, even ones run CMP2), P4 flag wait removed
# speedup vs baseline: 1.2032x; 1.0030x over previous
.LBB0_561:
	s_and_b64 s[2:3], s[4:5], exec
	v_readlane_b32 s4, v255, 61
	v_mov_b32_e32 v64, v166
	v_readlane_b32 s12, v254, 5
	v_readlane_b32 s13, v254, 6
	v_readlane_b32 s14, v254, 7
	v_readlane_b32 s15, v254, 8
	v_readlane_b32 s16, v254, 9
	v_readlane_b32 s17, v254, 10
	s_waitcnt lgkmcnt(0)
	s_barrier
	v_readlane_b32 s18, v254, 11
	v_and_b32_e32 v65, 31, v64
	v_readlane_b32 s19, v254, 12
	s_mov_b64 s[12:13], s[16:17]
	v_readlane_b32 s5, v255, 62
	s_mov_b64 s[14:15], s[18:19]
	v_or3_b32 v66, v65, v174, s0
	s_cselect_b32 s5, s13, s15
	s_cselect_b32 s4, s12, s14
	v_lshlrev_b32_e32 v68, 2, v66
	global_load_dword v69, v68, s[4:5]
	v_readlane_b32 s36, v254, 13
	v_readlane_b32 s48, v254, 25
	v_readlane_b32 s49, v254, 26
	v_readlane_b32 s50, v254, 27
	v_readlane_b32 s51, v254, 28
	v_readlane_b32 s2, v255, 12
	s_cselect_b32 s1, s49, s51
	s_cselect_b32 s0, s48, s50
	s_and_b32 s2, s2, 30
	v_lshrrev_b32_e32 v64, 3, v64
	v_add_lshl_u32 v67, v172, s2, 6
	v_mov_b32_e32 v65, 0
	v_and_or_b32 v70, v64, 4, v67
	v_lshlrev_b32_e32 v64, 1, v66
	v_lshl_add_u64 v[66:67], s[0:1], 0, v[64:65]
	v_mul_u32_u24_e32 v64, 0x280, v70
	v_lshl_add_u64 v[64:65], v[66:67], 0, v[64:65]
	v_readlane_b32 s6, v255, 63
	v_readlane_b32 s7, v254, 0
	global_load_dword v68, v68, s[4:5] offset:128
	v_readlane_b32 s8, v254, 1
	v_readlane_b32 s9, v254, 2
	s_movk_i32 s2, 0x1000
	v_readlane_b32 s10, v254, 3
	v_readlane_b32 s11, v254, 4
	v_readlane_b32 s37, v254, 14
	v_readlane_b32 s38, v254, 15
	v_readlane_b32 s39, v254, 16
	v_readlane_b32 s40, v254, 17
	v_readlane_b32 s41, v254, 18
	v_readlane_b32 s42, v254, 19
	v_readlane_b32 s43, v254, 20
	v_readlane_b32 s44, v254, 21
	v_readlane_b32 s45, v254, 22
	v_readlane_b32 s46, v254, 23
	v_readlane_b32 s47, v254, 24
	s_waitcnt vmcnt(0)
	v_add_f32_e32 v48, v48, v69
	v_add_f32_e32 v49, v49, v69
	v_mul_f32_e32 v66, 0xbfb8aa3b, v48
	v_add_f32_e32 v50, v50, v69
	v_mul_f32_e32 v67, 0xbfb8aa3b, v49
	v_exp_f32_e32 v66, v66
	v_add_f32_e32 v51, v51, v69
	v_mul_f32_e32 v70, 0xbfb8aa3b, v50
	v_exp_f32_e32 v67, v67
	v_mul_f32_e32 v71, 0xbfb8aa3b, v51
	v_exp_f32_e32 v70, v70
	v_exp_f32_e32 v71, v71
	v_add_f32_e32 v66, 1.0, v66
	v_add_f32_e32 v67, 1.0, v67
	v_div_scale_f32 v73, s[0:1], v66, v66, v48
	v_add_f32_e32 v70, 1.0, v70
	v_div_scale_f32 v75, s[0:1], v67, v67, v49
	v_rcp_f32_e32 v82, v73
	v_add_f32_e32 v71, 1.0, v71
	v_div_scale_f32 v77, s[0:1], v70, v70, v50
	v_rcp_f32_e32 v83, v75
	v_div_scale_f32 v79, s[0:1], v71, v71, v51
	v_rcp_f32_e32 v84, v77
	v_rcp_f32_e32 v85, v79
	v_add_f32_e32 v52, v52, v69
	v_fma_f32 v87, -v73, v82, 1.0
	v_mul_f32_e32 v72, 0xbfb8aa3b, v52
	v_div_scale_f32 v74, vcc, v48, v66, v48
	v_fma_f32 v88, -v75, v83, 1.0
	v_fmac_f32_e32 v82, v87, v82
	v_exp_f32_e32 v72, v72
	v_div_scale_f32 v76, s[4:5], v49, v67, v49
	v_fma_f32 v89, -v77, v84, 1.0
	v_fmac_f32_e32 v83, v88, v83
	v_mul_f32_e32 v87, v74, v82
	v_div_scale_f32 v78, s[6:7], v50, v70, v50
	v_fma_f32 v90, -v79, v85, 1.0
	v_fmac_f32_e32 v84, v89, v84
	v_mul_f32_e32 v88, v76, v83
	v_fma_f32 v91, -v73, v87, v74
	v_div_scale_f32 v80, s[8:9], v51, v71, v51
	v_fmac_f32_e32 v85, v90, v85
	v_mul_f32_e32 v89, v78, v84
	v_fma_f32 v92, -v75, v88, v76
	v_fmac_f32_e32 v87, v91, v82
	v_mul_f32_e32 v90, v80, v85
	v_fma_f32 v93, -v77, v89, v78
	v_fmac_f32_e32 v88, v92, v83
	v_fma_f32 v73, -v73, v87, v74
	v_add_f32_e32 v72, 1.0, v72
	v_fma_f32 v94, -v79, v90, v80
	v_fmac_f32_e32 v89, v93, v84
	v_fma_f32 v74, -v75, v88, v76
	v_div_fmas_f32 v73, v73, v82, v87
	s_mov_b64 vcc, s[4:5]
	v_div_scale_f32 v81, s[0:1], v72, v72, v52
	v_fmac_f32_e32 v90, v94, v85
	v_fma_f32 v75, -v77, v89, v78
	v_div_fixup_f32 v48, v73, v66, v48
	v_div_fmas_f32 v66, v74, v83, v88
	s_mov_b64 vcc, s[6:7]
	v_rcp_f32_e32 v86, v81
	v_fma_f32 v76, -v79, v90, v80
	v_cvt_pk_bf16_f32 v48, v48, s0
	v_div_fixup_f32 v49, v66, v67, v49
	v_div_fmas_f32 v66, v75, v84, v89
	s_mov_b64 vcc, s[8:9]
	global_store_short v[64:65], v48, off
	v_cvt_pk_bf16_f32 v48, v49, s0
	v_div_fixup_f32 v49, v66, v70, v50
	v_div_fmas_f32 v50, v76, v85, v90
	global_store_short v[64:65], v48, off offset:640
	v_cvt_pk_bf16_f32 v48, v49, s0
	v_div_fixup_f32 v49, v50, v71, v51
	global_store_short v[64:65], v48, off offset:1280
	v_cvt_pk_bf16_f32 v48, v49, s0
	global_store_short v[64:65], v48, off offset:1920
	v_fma_f32 v48, -v81, v86, 1.0
	v_fmac_f32_e32 v86, v48, v86
	v_div_scale_f32 v48, vcc, v52, v72, v52
	v_mul_f32_e32 v49, v48, v86
	v_fma_f32 v50, -v81, v49, v48
	v_fmac_f32_e32 v49, v50, v86
	v_fma_f32 v48, -v81, v49, v48
	v_div_fmas_f32 v48, v48, v86, v49
	v_add_f32_e32 v49, v53, v69
	v_mul_f32_e32 v50, 0xbfb8aa3b, v49
	v_exp_f32_e32 v50, v50
	v_div_fixup_f32 v48, v48, v72, v52
	v_cvt_pk_bf16_f32 v48, v48, s0
	v_add_co_u32_e32 v66, vcc, s2, v64
	v_add_f32_e32 v50, 1.0, v50
	v_div_scale_f32 v51, s[0:1], v50, v50, v49
	v_rcp_f32_e32 v52, v51
	v_addc_co_u32_e32 v67, vcc, 0, v65, vcc
	global_store_short v[66:67], v48, off offset:1024
	v_fma_f32 v48, -v51, v52, 1.0
	v_fmac_f32_e32 v52, v48, v52
	v_div_scale_f32 v48, vcc, v49, v50, v49
	v_mul_f32_e32 v53, v48, v52
	v_fma_f32 v70, -v51, v53, v48
	v_add_f32_e32 v54, v54, v69
	v_fmac_f32_e32 v53, v70, v52
	v_mul_f32_e32 v70, 0xbfb8aa3b, v54
	v_exp_f32_e32 v70, v70
	v_fma_f32 v48, -v51, v53, v48
	v_div_fmas_f32 v48, v48, v52, v53
	v_div_fixup_f32 v48, v48, v50, v49
	v_add_f32_e32 v51, 1.0, v70
	v_div_scale_f32 v52, s[0:1], v51, v51, v54
	v_rcp_f32_e32 v53, v52
	s_nop 0
	v_cvt_pk_bf16_f32 v48, v48, s0
	global_store_short v[66:67], v48, off offset:1664
	s_movk_i32 s2, 0x2000
	v_fma_f32 v48, -v52, v53, 1.0
	v_fmac_f32_e32 v53, v48, v53
	v_div_scale_f32 v48, vcc, v54, v51, v54
	v_mul_f32_e32 v49, v48, v53
	v_fma_f32 v50, -v52, v49, v48
	v_fmac_f32_e32 v49, v50, v53
	v_add_f32_e32 v50, v55, v69
	v_mul_f32_e32 v55, 0xbfb8aa3b, v50
	v_exp_f32_e32 v55, v55
	v_fma_f32 v48, -v52, v49, v48
	v_div_fmas_f32 v48, v48, v53, v49
	v_div_fixup_f32 v48, v48, v51, v54
	v_add_f32_e32 v49, 1.0, v55
	v_div_scale_f32 v52, s[0:1], v49, v49, v50
	v_rcp_f32_e32 v53, v52
	s_nop 0
	v_cvt_pk_bf16_f32 v48, v48, s0
	global_store_short v[66:67], v48, off offset:2304
	v_add_f32_e32 v32, v32, v68
	v_fma_f32 v48, -v52, v53, 1.0
	v_fmac_f32_e32 v53, v48, v53
	v_div_scale_f32 v48, vcc, v50, v49, v50
	v_mul_f32_e32 v51, v48, v53
	v_fma_f32 v54, -v52, v51, v48
	v_fmac_f32_e32 v51, v54, v53
	v_add_f32_e32 v54, v56, v69
	v_mul_f32_e32 v55, 0xbfb8aa3b, v54
	v_exp_f32_e32 v55, v55
	v_fma_f32 v48, -v52, v51, v48
	v_div_fmas_f32 v48, v48, v53, v51
	v_div_fixup_f32 v48, v48, v49, v50
	v_add_f32_e32 v51, 1.0, v55
	v_div_scale_f32 v52, s[0:1], v51, v51, v54
	v_rcp_f32_e32 v53, v52
	s_nop 0
	v_cvt_pk_bf16_f32 v48, v48, s0
	global_store_short v[66:67], v48, off offset:2944
	v_add_f32_e32 v33, v33, v68
	v_fma_f32 v48, -v52, v53, 1.0
	v_fmac_f32_e32 v53, v48, v53
	v_div_scale_f32 v48, vcc, v54, v51, v54
	v_mul_f32_e32 v49, v48, v53
	v_fma_f32 v50, -v52, v49, v48
	v_fmac_f32_e32 v49, v50, v53
	v_fma_f32 v48, -v52, v49, v48
	v_add_f32_e32 v50, v57, v69
	v_div_fmas_f32 v48, v48, v53, v49
	v_mul_f32_e32 v49, 0xbfb8aa3b, v50
	v_exp_f32_e32 v49, v49
	v_div_fixup_f32 v48, v48, v51, v54
	v_cvt_pk_bf16_f32 v51, v48, s0
	v_add_co_u32_e32 v48, vcc, s2, v64
	v_add_f32_e32 v52, 1.0, v49
	v_div_scale_f32 v53, s[0:1], v52, v52, v50
	v_rcp_f32_e32 v54, v53
	v_addc_co_u32_e32 v49, vcc, 0, v65, vcc
	global_store_short v[48:49], v51, off offset:2048
	v_fma_f32 v51, -v53, v54, 1.0
	v_fmac_f32_e32 v54, v51, v54
	v_div_scale_f32 v51, vcc, v50, v52, v50
	v_mul_f32_e32 v55, v51, v54
	v_fma_f32 v56, -v53, v55, v51
	v_fmac_f32_e32 v55, v56, v54
	v_add_f32_e32 v56, v58, v69
	v_mul_f32_e32 v57, 0xbfb8aa3b, v56
	v_exp_f32_e32 v57, v57
	v_fma_f32 v51, -v53, v55, v51
	v_div_fmas_f32 v51, v51, v54, v55
	v_div_fixup_f32 v50, v51, v52, v50
	v_add_f32_e32 v53, 1.0, v57
	v_div_scale_f32 v54, s[0:1], v53, v53, v56
	v_rcp_f32_e32 v55, v54
	s_nop 0
	v_cvt_pk_bf16_f32 v50, v50, s0
	global_store_short v[48:49], v50, off offset:2688
	s_movk_i32 s2, 0x3000
	v_fma_f32 v50, -v54, v55, 1.0
	v_fmac_f32_e32 v55, v50, v55
	v_div_scale_f32 v50, vcc, v56, v53, v56
	v_mul_f32_e32 v51, v50, v55
	v_fma_f32 v52, -v54, v51, v50
	v_fmac_f32_e32 v51, v52, v55
	v_add_f32_e32 v52, v59, v69
	v_mul_f32_e32 v57, 0xbfb8aa3b, v52
	v_exp_f32_e32 v57, v57
	v_fma_f32 v50, -v54, v51, v50
	v_div_fmas_f32 v50, v50, v55, v51
	v_div_fixup_f32 v50, v50, v53, v56
	v_add_f32_e32 v51, 1.0, v57
	v_div_scale_f32 v54, s[0:1], v51, v51, v52
	v_rcp_f32_e32 v55, v54
	s_nop 0
	v_cvt_pk_bf16_f32 v50, v50, s0
	global_store_short v[48:49], v50, off offset:3328
	v_add_f32_e32 v34, v34, v68
	v_fma_f32 v50, -v54, v55, 1.0
	v_fmac_f32_e32 v55, v50, v55
	v_div_scale_f32 v50, vcc, v52, v51, v52
	v_mul_f32_e32 v53, v50, v55
	v_fma_f32 v56, -v54, v53, v50
	v_fmac_f32_e32 v53, v56, v55
	v_add_f32_e32 v56, v60, v69
	v_mul_f32_e32 v57, 0xbfb8aa3b, v56
	v_exp_f32_e32 v57, v57
	v_fma_f32 v50, -v54, v53, v50
	v_div_fmas_f32 v50, v50, v55, v53
	v_div_fixup_f32 v50, v50, v51, v52
	v_add_f32_e32 v53, 1.0, v57
	v_div_scale_f32 v54, s[0:1], v53, v53, v56
	v_rcp_f32_e32 v55, v54
	s_nop 0
	v_cvt_pk_bf16_f32 v50, v50, s0
	global_store_short v[48:49], v50, off offset:3968
	v_add_f32_e32 v35, v35, v68
	v_fma_f32 v50, -v54, v55, 1.0
	v_fmac_f32_e32 v55, v50, v55
	v_div_scale_f32 v50, vcc, v56, v53, v56
	v_mul_f32_e32 v51, v50, v55
	v_fma_f32 v52, -v54, v51, v50
	v_fmac_f32_e32 v51, v52, v55
	v_fma_f32 v50, -v54, v51, v50
	v_div_fmas_f32 v50, v50, v55, v51
	v_add_f32_e32 v51, v61, v69
	v_mul_f32_e32 v52, 0xbfb8aa3b, v51
	v_exp_f32_e32 v52, v52
	v_div_fixup_f32 v50, v50, v53, v56
	v_cvt_pk_bf16_f32 v50, v50, s0
	v_add_f32_e32 v36, v36, v68
	v_add_f32_e32 v54, 1.0, v52
	v_div_scale_f32 v55, s[0:1], v54, v54, v51
	v_rcp_f32_e32 v56, v55
	v_add_co_u32_e32 v52, vcc, s2, v64
	s_movk_i32 s2, 0x4000
	s_nop 0
	v_addc_co_u32_e32 v53, vcc, 0, v65, vcc
	global_store_short v[52:53], v50, off offset:3072
	v_fma_f32 v50, -v55, v56, 1.0
	v_fmac_f32_e32 v56, v50, v56
	v_div_scale_f32 v50, vcc, v51, v54, v51
	v_mul_f32_e32 v57, v50, v56
	v_fma_f32 v58, -v55, v57, v50
	v_fmac_f32_e32 v57, v58, v56
	v_add_f32_e32 v58, v62, v69
	v_mul_f32_e32 v59, 0xbfb8aa3b, v58
	v_exp_f32_e32 v59, v59
	v_fma_f32 v50, -v55, v57, v50
	v_div_fmas_f32 v50, v50, v56, v57
	v_div_fixup_f32 v50, v50, v54, v51
	v_add_f32_e32 v55, 1.0, v59
	v_div_scale_f32 v56, s[0:1], v55, v55, v58
	v_rcp_f32_e32 v57, v56
	s_nop 0
	v_cvt_pk_bf16_f32 v50, v50, s0
	global_store_short v[52:53], v50, off offset:3712
	v_add_f32_e32 v16, v16, v69
	v_fma_f32 v50, -v56, v57, 1.0
	v_fmac_f32_e32 v57, v50, v57
	v_div_scale_f32 v50, vcc, v58, v55, v58
	v_mul_f32_e32 v51, v50, v57
	v_fma_f32 v54, -v56, v51, v50
	v_fmac_f32_e32 v51, v54, v57
	v_fma_f32 v50, -v56, v51, v50
	v_add_f32_e32 v54, v63, v69
	v_div_fmas_f32 v50, v50, v57, v51
	v_mul_f32_e32 v51, 0xbfb8aa3b, v54
	v_exp_f32_e32 v51, v51
	v_div_fixup_f32 v50, v50, v55, v58
	v_cvt_pk_bf16_f32 v55, v50, s0
	v_add_co_u32_e32 v50, vcc, s2, v64
	v_add_f32_e32 v56, 1.0, v51
	v_div_scale_f32 v57, s[0:1], v56, v56, v54
	v_rcp_f32_e32 v58, v57
	v_addc_co_u32_e32 v51, vcc, 0, v65, vcc
	global_store_short v[50:51], v55, off offset:256
	v_fma_f32 v55, -v57, v58, 1.0
	v_fmac_f32_e32 v58, v55, v58
	v_div_scale_f32 v55, vcc, v54, v56, v54
	v_mul_f32_e32 v59, v55, v58
	v_fma_f32 v60, -v57, v59, v55
	v_fmac_f32_e32 v59, v60, v58
	v_mul_f32_e32 v60, 0xbfb8aa3b, v32
	v_exp_f32_e32 v60, v60
	v_fma_f32 v55, -v57, v59, v55
	v_div_fmas_f32 v55, v55, v58, v59
	v_div_fixup_f32 v54, v55, v56, v54
	v_add_f32_e32 v57, 1.0, v60
	v_div_scale_f32 v58, s[0:1], v57, v57, v32
	v_rcp_f32_e32 v59, v58
	s_nop 0
	v_cvt_pk_bf16_f32 v54, v54, s0
	global_store_short v[50:51], v54, off offset:896
	s_movk_i32 s2, 0x5000
	v_fma_f32 v54, -v58, v59, 1.0
	v_fmac_f32_e32 v59, v54, v59
	v_div_scale_f32 v54, vcc, v32, v57, v32
	v_mul_f32_e32 v55, v54, v59
	v_fma_f32 v56, -v58, v55, v54
	v_fmac_f32_e32 v55, v56, v59
	v_mul_f32_e32 v56, 0xbfb8aa3b, v33
	v_exp_f32_e32 v56, v56
	v_fma_f32 v54, -v58, v55, v54
	v_div_fmas_f32 v54, v54, v59, v55
	v_div_fixup_f32 v32, v54, v57, v32
	v_add_f32_e32 v55, 1.0, v56
	v_div_scale_f32 v56, s[0:1], v55, v55, v33
	v_rcp_f32_e32 v58, v56
	s_nop 0
	v_cvt_pk_bf16_f32 v32, v32, s0
	global_store_short v[64:65], v32, off offset:64
	v_add_f32_e32 v18, v18, v69
	v_fma_f32 v32, -v56, v58, 1.0
	v_fmac_f32_e32 v58, v32, v58
	v_div_scale_f32 v32, vcc, v33, v55, v33
	v_mul_f32_e32 v54, v32, v58
	v_fma_f32 v57, -v56, v54, v32
	v_fmac_f32_e32 v54, v57, v58
	v_mul_f32_e32 v57, 0xbfb8aa3b, v34
	v_exp_f32_e32 v57, v57
	v_fma_f32 v32, -v56, v54, v32
	v_div_fmas_f32 v32, v32, v58, v54
	v_div_fixup_f32 v32, v32, v55, v33
	v_add_f32_e32 v54, 1.0, v57
	v_div_scale_f32 v56, s[0:1], v54, v54, v34
	v_rcp_f32_e32 v57, v56
	s_nop 0
	v_cvt_pk_bf16_f32 v32, v32, s0
	global_store_short v[64:65], v32, off offset:704
	v_add_f32_e32 v19, v19, v69
	v_fma_f32 v32, -v56, v57, 1.0
	v_fmac_f32_e32 v57, v32, v57
	v_div_scale_f32 v32, vcc, v34, v54, v34
	v_mul_f32_e32 v33, v32, v57
	v_fma_f32 v55, -v56, v33, v32
	v_fmac_f32_e32 v33, v55, v57
	v_mul_f32_e32 v55, 0xbfb8aa3b, v35
	v_exp_f32_e32 v55, v55
	v_fma_f32 v32, -v56, v33, v32
	v_div_fmas_f32 v32, v32, v57, v33
	v_div_fixup_f32 v32, v32, v54, v34
	v_add_f32_e32 v33, 1.0, v55
	v_div_scale_f32 v55, s[0:1], v33, v33, v35
	v_rcp_f32_e32 v56, v55
	s_nop 0
	v_cvt_pk_bf16_f32 v32, v32, s0
	global_store_short v[64:65], v32, off offset:1344
	v_add_f32_e32 v20, v20, v69
	v_fma_f32 v32, -v55, v56, 1.0
	v_fmac_f32_e32 v56, v32, v56
	v_div_scale_f32 v32, vcc, v35, v33, v35
	v_mul_f32_e32 v34, v32, v56
	v_fma_f32 v54, -v55, v34, v32
	v_fmac_f32_e32 v34, v54, v56
	v_mul_f32_e32 v54, 0xbfb8aa3b, v36
	v_exp_f32_e32 v54, v54
	v_fma_f32 v32, -v55, v34, v32
	v_div_fmas_f32 v32, v32, v56, v34
	v_div_fixup_f32 v32, v32, v33, v35
	v_add_f32_e32 v34, 1.0, v54
	v_div_scale_f32 v54, s[0:1], v34, v34, v36
	v_rcp_f32_e32 v55, v54
	s_nop 0
	v_cvt_pk_bf16_f32 v32, v32, s0
	global_store_short v[64:65], v32, off offset:1984
	v_add_f32_e32 v21, v21, v69
	v_fma_f32 v32, -v54, v55, 1.0
	v_fmac_f32_e32 v55, v32, v55
	v_div_scale_f32 v32, vcc, v36, v34, v36
	v_mul_f32_e32 v33, v32, v55
	v_fma_f32 v35, -v54, v33, v32
	v_fmac_f32_e32 v33, v35, v55
	v_add_f32_e32 v35, v37, v68
	v_mul_f32_e32 v37, 0xbfb8aa3b, v35
	v_exp_f32_e32 v37, v37
	v_fma_f32 v32, -v54, v33, v32
	v_div_fmas_f32 v32, v32, v55, v33
	v_div_fixup_f32 v32, v32, v34, v36
	v_add_f32_e32 v33, 1.0, v37
	v_div_scale_f32 v37, s[0:1], v33, v33, v35
	v_rcp_f32_e32 v54, v37
	s_nop 0
	v_cvt_pk_bf16_f32 v32, v32, s0
	global_store_short v[66:67], v32, off offset:1088
	v_add_f32_e32 v22, v22, v69
	v_fma_f32 v32, -v37, v54, 1.0
	v_fmac_f32_e32 v54, v32, v54
	v_div_scale_f32 v32, vcc, v35, v33, v35
	v_mul_f32_e32 v34, v32, v54
	v_fma_f32 v36, -v37, v34, v32
	v_fmac_f32_e32 v34, v36, v54
	v_add_f32_e32 v36, v38, v68
	v_mul_f32_e32 v38, 0xbfb8aa3b, v36
	v_exp_f32_e32 v38, v38
	v_fma_f32 v32, -v37, v34, v32
	v_div_fmas_f32 v32, v32, v54, v34
	v_div_fixup_f32 v32, v32, v33, v35
	v_add_f32_e32 v34, 1.0, v38
	v_div_scale_f32 v37, s[0:1], v34, v34, v36
	v_rcp_f32_e32 v38, v37
	s_nop 0
	v_cvt_pk_bf16_f32 v32, v32, s0
	global_store_short v[66:67], v32, off offset:1728
	v_add_f32_e32 v23, v23, v69
	v_fma_f32 v32, -v37, v38, 1.0
	v_fmac_f32_e32 v38, v32, v38
	v_div_scale_f32 v32, vcc, v36, v34, v36
	v_mul_f32_e32 v33, v32, v38
	v_fma_f32 v35, -v37, v33, v32
	v_fmac_f32_e32 v33, v35, v38
	v_add_f32_e32 v35, v39, v68
	v_mul_f32_e32 v39, 0xbfb8aa3b, v35
	v_exp_f32_e32 v39, v39
	v_fma_f32 v32, -v37, v33, v32
	v_div_fmas_f32 v32, v32, v38, v33
	v_div_fixup_f32 v32, v32, v34, v36
	v_add_f32_e32 v33, 1.0, v39
	v_div_scale_f32 v37, s[0:1], v33, v33, v35
	v_rcp_f32_e32 v38, v37
	s_nop 0
	v_cvt_pk_bf16_f32 v32, v32, s0
	global_store_short v[66:67], v32, off offset:2368
	v_add_f32_e32 v24, v24, v69
	v_fma_f32 v32, -v37, v38, 1.0
	v_fmac_f32_e32 v38, v32, v38
	v_div_scale_f32 v32, vcc, v35, v33, v35
	v_mul_f32_e32 v34, v32, v38
	v_fma_f32 v36, -v37, v34, v32
	v_fmac_f32_e32 v34, v36, v38
	v_add_f32_e32 v36, v40, v68
	v_mul_f32_e32 v39, 0xbfb8aa3b, v36
	v_exp_f32_e32 v39, v39
	v_fma_f32 v32, -v37, v34, v32
	v_div_fmas_f32 v32, v32, v38, v34
	v_div_fixup_f32 v32, v32, v33, v35
	v_add_f32_e32 v34, 1.0, v39
	v_div_scale_f32 v37, s[0:1], v34, v34, v36
	v_rcp_f32_e32 v38, v37
	s_nop 0
	v_cvt_pk_bf16_f32 v32, v32, s0
	global_store_short v[66:67], v32, off offset:3008
	v_add_f32_e32 v26, v26, v69
	v_fma_f32 v32, -v37, v38, 1.0
	v_fmac_f32_e32 v38, v32, v38
	v_div_scale_f32 v32, vcc, v36, v34, v36
	v_mul_f32_e32 v33, v32, v38
	v_fma_f32 v35, -v37, v33, v32
	v_fmac_f32_e32 v33, v35, v38
	v_add_f32_e32 v35, v41, v68
	v_mul_f32_e32 v39, 0xbfb8aa3b, v35
	v_exp_f32_e32 v39, v39
	v_fma_f32 v32, -v37, v33, v32
	v_div_fmas_f32 v32, v32, v38, v33
	v_div_fixup_f32 v32, v32, v34, v36
	v_add_f32_e32 v33, 1.0, v39
	v_div_scale_f32 v37, s[0:1], v33, v33, v35
	v_rcp_f32_e32 v38, v37
	s_nop 0
	v_cvt_pk_bf16_f32 v32, v32, s0
	global_store_short v[48:49], v32, off offset:2112
	v_add_f32_e32 v30, v30, v69
	v_fma_f32 v32, -v37, v38, 1.0
	v_fmac_f32_e32 v38, v32, v38
	v_div_scale_f32 v32, vcc, v35, v33, v35
	v_mul_f32_e32 v34, v32, v38
	v_fma_f32 v36, -v37, v34, v32
	v_fmac_f32_e32 v34, v36, v38
	v_add_f32_e32 v36, v42, v68
	v_mul_f32_e32 v39, 0xbfb8aa3b, v36
	v_exp_f32_e32 v39, v39
	v_fma_f32 v32, -v37, v34, v32
	v_div_fmas_f32 v32, v32, v38, v34
	v_div_fixup_f32 v32, v32, v33, v35
	v_add_f32_e32 v34, 1.0, v39
	v_div_scale_f32 v37, s[0:1], v34, v34, v36
	v_rcp_f32_e32 v38, v37
	s_nop 0
	v_cvt_pk_bf16_f32 v32, v32, s0
	global_store_short v[48:49], v32, off offset:2752
	v_add_f32_e32 v0, v0, v68
	v_fma_f32 v32, -v37, v38, 1.0
	v_fmac_f32_e32 v38, v32, v38
	v_div_scale_f32 v32, vcc, v36, v34, v36
	v_mul_f32_e32 v33, v32, v38
	v_fma_f32 v35, -v37, v33, v32
	v_fmac_f32_e32 v33, v35, v38
	v_add_f32_e32 v35, v43, v68
	v_mul_f32_e32 v39, 0xbfb8aa3b, v35
	v_exp_f32_e32 v39, v39
	v_fma_f32 v32, -v37, v33, v32
	v_div_fmas_f32 v32, v32, v38, v33
	v_div_fixup_f32 v32, v32, v34, v36
	v_add_f32_e32 v33, 1.0, v39
	v_div_scale_f32 v37, s[0:1], v33, v33, v35
	v_rcp_f32_e32 v38, v37
	s_nop 0
	v_cvt_pk_bf16_f32 v32, v32, s0
	global_store_short v[48:49], v32, off offset:3392
	v_add_f32_e32 v1, v1, v68
	v_fma_f32 v32, -v37, v38, 1.0
	v_fmac_f32_e32 v38, v32, v38
	v_div_scale_f32 v32, vcc, v35, v33, v35
	v_mul_f32_e32 v34, v32, v38
	v_fma_f32 v36, -v37, v34, v32
	v_fmac_f32_e32 v34, v36, v38
	v_add_f32_e32 v36, v44, v68
	v_mul_f32_e32 v39, 0xbfb8aa3b, v36
	v_exp_f32_e32 v39, v39
	v_fma_f32 v32, -v37, v34, v32
	v_div_fmas_f32 v32, v32, v38, v34
	v_div_fixup_f32 v32, v32, v33, v35
	v_add_f32_e32 v34, 1.0, v39
	v_div_scale_f32 v37, s[0:1], v34, v34, v36
	v_rcp_f32_e32 v38, v37
	s_nop 0
	v_cvt_pk_bf16_f32 v32, v32, s0
	global_store_short v[48:49], v32, off offset:4032
	v_add_f32_e32 v2, v2, v68
	v_fma_f32 v32, -v37, v38, 1.0
	v_fmac_f32_e32 v38, v32, v38
	v_div_scale_f32 v32, vcc, v36, v34, v36
	v_mul_f32_e32 v33, v32, v38
	v_fma_f32 v35, -v37, v33, v32
	v_fmac_f32_e32 v33, v35, v38
	v_add_f32_e32 v35, v45, v68
	v_mul_f32_e32 v39, 0xbfb8aa3b, v35
	v_exp_f32_e32 v39, v39
	v_fma_f32 v32, -v37, v33, v32
	v_div_fmas_f32 v32, v32, v38, v33
	v_div_fixup_f32 v32, v32, v34, v36
	v_add_f32_e32 v33, 1.0, v39
	v_div_scale_f32 v37, s[0:1], v33, v33, v35
	v_rcp_f32_e32 v38, v37
	s_nop 0
	v_cvt_pk_bf16_f32 v32, v32, s0
	global_store_short v[52:53], v32, off offset:3136
	v_add_f32_e32 v3, v3, v68
	v_fma_f32 v32, -v37, v38, 1.0
	v_fmac_f32_e32 v38, v32, v38
	v_div_scale_f32 v32, vcc, v35, v33, v35
	v_mul_f32_e32 v34, v32, v38
	v_fma_f32 v36, -v37, v34, v32
	v_fmac_f32_e32 v34, v36, v38
	v_add_f32_e32 v36, v46, v68
	v_mul_f32_e32 v39, 0xbfb8aa3b, v36
	v_exp_f32_e32 v39, v39
	v_fma_f32 v32, -v37, v34, v32
	v_div_fmas_f32 v32, v32, v38, v34
	v_div_fixup_f32 v32, v32, v33, v35
	v_add_f32_e32 v34, 1.0, v39
	v_div_scale_f32 v37, s[0:1], v34, v34, v36
	v_rcp_f32_e32 v38, v37
	s_nop 0
	v_cvt_pk_bf16_f32 v32, v32, s0
	global_store_short v[52:53], v32, off offset:3776
	v_add_f32_e32 v4, v4, v68
	v_fma_f32 v32, -v37, v38, 1.0
	v_fmac_f32_e32 v38, v32, v38
	v_div_scale_f32 v32, vcc, v36, v34, v36
	v_mul_f32_e32 v33, v32, v38
	v_fma_f32 v35, -v37, v33, v32
	v_fmac_f32_e32 v33, v35, v38
	v_add_f32_e32 v35, v47, v68
	v_mul_f32_e32 v39, 0xbfb8aa3b, v35
	v_exp_f32_e32 v39, v39
	v_fma_f32 v32, -v37, v33, v32
	v_div_fmas_f32 v32, v32, v38, v33
	v_div_fixup_f32 v32, v32, v34, v36
	v_add_f32_e32 v33, 1.0, v39
	v_div_scale_f32 v37, s[0:1], v33, v33, v35
	v_rcp_f32_e32 v38, v37
	s_nop 0
	v_cvt_pk_bf16_f32 v32, v32, s0
	global_store_short v[50:51], v32, off offset:320
	v_fma_f32 v32, -v37, v38, 1.0
	v_fmac_f32_e32 v38, v32, v38
	v_div_scale_f32 v32, vcc, v35, v33, v35
	v_mul_f32_e32 v34, v32, v38
	v_fma_f32 v36, -v37, v34, v32
	v_fmac_f32_e32 v34, v36, v38
	v_mul_f32_e32 v36, 0xbfb8aa3b, v16
	v_exp_f32_e32 v36, v36
	v_fma_f32 v32, -v37, v34, v32
	v_div_fmas_f32 v32, v32, v38, v34
	v_div_fixup_f32 v32, v32, v33, v35
	v_add_f32_e32 v34, 1.0, v36
	v_div_scale_f32 v36, s[0:1], v34, v34, v16
	v_rcp_f32_e32 v37, v36
	s_nop 0
	v_cvt_pk_bf16_f32 v32, v32, s0
	global_store_short v[50:51], v32, off offset:960
	v_fma_f32 v32, -v36, v37, 1.0
	v_fmac_f32_e32 v37, v32, v37
	v_div_scale_f32 v32, vcc, v16, v34, v16
	v_mul_f32_e32 v33, v32, v37
	v_fma_f32 v35, -v36, v33, v32
	v_fmac_f32_e32 v33, v35, v37
	v_fma_f32 v32, -v36, v33, v32
	v_div_fmas_f32 v32, v32, v37, v33
	v_add_f32_e32 v33, v17, v69
	v_mul_f32_e32 v17, 0xbfb8aa3b, v33
	v_exp_f32_e32 v17, v17
	v_div_fixup_f32 v16, v32, v34, v16
	v_cvt_pk_bf16_f32 v32, v16, s0
	v_add_co_u32_e32 v16, vcc, s2, v64
	v_add_f32_e32 v34, 1.0, v17
	v_div_scale_f32 v35, s[0:1], v34, v34, v33
	v_rcp_f32_e32 v36, v35
	v_addc_co_u32_e32 v17, vcc, 0, v65, vcc
	global_store_short v[16:17], v32, off
	v_fma_f32 v32, -v35, v36, 1.0
	v_fmac_f32_e32 v36, v32, v36
	v_div_scale_f32 v32, vcc, v33, v34, v33
	v_mul_f32_e32 v37, v32, v36
	v_fma_f32 v38, -v35, v37, v32
	v_fmac_f32_e32 v37, v38, v36
	v_mul_f32_e32 v38, 0xbfb8aa3b, v18
	v_exp_f32_e32 v38, v38
	v_fma_f32 v32, -v35, v37, v32
	v_div_fmas_f32 v32, v32, v36, v37
	v_div_fixup_f32 v32, v32, v34, v33
	v_add_f32_e32 v35, 1.0, v38
	v_div_scale_f32 v36, s[0:1], v35, v35, v18
	v_rcp_f32_e32 v37, v36
	s_nop 0
	v_cvt_pk_bf16_f32 v32, v32, s0
	global_store_short v[16:17], v32, off offset:640
	s_movk_i32 s2, 0x6000
	v_fma_f32 v32, -v36, v37, 1.0
	v_fmac_f32_e32 v37, v32, v37
	v_div_scale_f32 v32, vcc, v18, v35, v18
	v_mul_f32_e32 v33, v32, v37
	v_fma_f32 v34, -v36, v33, v32
	v_fmac_f32_e32 v33, v34, v37
	v_mul_f32_e32 v34, 0xbfb8aa3b, v19
	v_exp_f32_e32 v34, v34
	v_fma_f32 v32, -v36, v33, v32
	v_div_fmas_f32 v32, v32, v37, v33
	v_div_fixup_f32 v18, v32, v35, v18
	v_add_f32_e32 v33, 1.0, v34
	v_div_scale_f32 v34, s[0:1], v33, v33, v19
	v_rcp_f32_e32 v36, v34
	s_nop 0
	v_cvt_pk_bf16_f32 v18, v18, s0
	global_store_short v[16:17], v18, off offset:1280
	v_fma_f32 v18, -v34, v36, 1.0
	v_fmac_f32_e32 v36, v18, v36
	v_div_scale_f32 v18, vcc, v19, v33, v19
	v_mul_f32_e32 v32, v18, v36
	v_fma_f32 v35, -v34, v32, v18
	v_fmac_f32_e32 v32, v35, v36
	v_mul_f32_e32 v35, 0xbfb8aa3b, v20
	v_exp_f32_e32 v35, v35
	v_fma_f32 v18, -v34, v32, v18
	v_div_fmas_f32 v18, v18, v36, v32
	v_div_fixup_f32 v18, v18, v33, v19
	v_add_f32_e32 v32, 1.0, v35
	v_div_scale_f32 v34, s[0:1], v32, v32, v20
	v_rcp_f32_e32 v35, v34
	s_nop 0
	v_cvt_pk_bf16_f32 v18, v18, s0
	global_store_short v[16:17], v18, off offset:1920
	v_fma_f32 v18, -v34, v35, 1.0
	v_fmac_f32_e32 v35, v18, v35
	v_div_scale_f32 v18, vcc, v20, v32, v20
	v_mul_f32_e32 v19, v18, v35
	v_fma_f32 v33, -v34, v19, v18
	v_fmac_f32_e32 v19, v33, v35
	v_fma_f32 v18, -v34, v19, v18
	v_div_fmas_f32 v18, v18, v35, v19
	v_mul_f32_e32 v19, 0xbfb8aa3b, v21
	v_exp_f32_e32 v19, v19
	v_div_fixup_f32 v18, v18, v32, v20
	v_cvt_pk_bf16_f32 v20, v18, s0
	v_add_co_u32_e32 v18, vcc, s2, v64
	v_add_f32_e32 v32, 1.0, v19
	v_div_scale_f32 v33, s[0:1], v32, v32, v21
	v_rcp_f32_e32 v34, v33
	v_addc_co_u32_e32 v19, vcc, 0, v65, vcc
	global_store_short v[18:19], v20, off offset:1024
	v_fma_f32 v20, -v33, v34, 1.0
	v_fmac_f32_e32 v34, v20, v34
	v_div_scale_f32 v20, vcc, v21, v32, v21
	v_mul_f32_e32 v35, v20, v34
	v_fma_f32 v36, -v33, v35, v20
	v_fmac_f32_e32 v35, v36, v34
	v_mul_f32_e32 v36, 0xbfb8aa3b, v22
	v_exp_f32_e32 v36, v36
	v_fma_f32 v20, -v33, v35, v20
	v_div_fmas_f32 v20, v20, v34, v35
	v_div_fixup_f32 v20, v20, v32, v21
	v_add_f32_e32 v33, 1.0, v36
	v_div_scale_f32 v34, s[0:1], v33, v33, v22
	v_rcp_f32_e32 v35, v34
	s_nop 0
	v_cvt_pk_bf16_f32 v20, v20, s0
	global_store_short v[18:19], v20, off offset:1664
	s_movk_i32 s2, 0x7000
	v_fma_f32 v20, -v34, v35, 1.0
	v_fmac_f32_e32 v35, v20, v35
	v_div_scale_f32 v20, vcc, v22, v33, v22
	v_mul_f32_e32 v21, v20, v35
	v_fma_f32 v32, -v34, v21, v20
	v_fmac_f32_e32 v21, v32, v35
	v_mul_f32_e32 v32, 0xbfb8aa3b, v23
	v_exp_f32_e32 v32, v32
	v_fma_f32 v20, -v34, v21, v20
	v_div_fmas_f32 v20, v20, v35, v21
	v_div_fixup_f32 v20, v20, v33, v22
	v_add_f32_e32 v21, 1.0, v32
	v_div_scale_f32 v32, s[0:1], v21, v21, v23
	v_rcp_f32_e32 v34, v32
	s_nop 0
	v_cvt_pk_bf16_f32 v20, v20, s0
	global_store_short v[18:19], v20, off offset:2304
	v_fma_f32 v20, -v32, v34, 1.0
	v_fmac_f32_e32 v34, v20, v34
	v_div_scale_f32 v20, vcc, v23, v21, v23
	v_mul_f32_e32 v22, v20, v34
	v_fma_f32 v33, -v32, v22, v20
	v_fmac_f32_e32 v22, v33, v34
	v_mul_f32_e32 v33, 0xbfb8aa3b, v24
	v_exp_f32_e32 v33, v33
	v_fma_f32 v20, -v32, v22, v20
	v_div_fmas_f32 v20, v20, v34, v22
	v_div_fixup_f32 v20, v20, v21, v23
	v_add_f32_e32 v22, 1.0, v33
	v_div_scale_f32 v32, s[0:1], v22, v22, v24
	v_rcp_f32_e32 v33, v32
	s_nop 0
	v_cvt_pk_bf16_f32 v20, v20, s0
	global_store_short v[18:19], v20, off offset:2944
	v_fma_f32 v20, -v32, v33, 1.0
	v_fmac_f32_e32 v33, v20, v33
	v_div_scale_f32 v20, vcc, v24, v22, v24
	v_mul_f32_e32 v21, v20, v33
	v_fma_f32 v23, -v32, v21, v20
	v_fmac_f32_e32 v21, v23, v33
	v_fma_f32 v20, -v32, v21, v20
	v_add_f32_e32 v23, v25, v69
	v_div_fmas_f32 v20, v20, v33, v21
	v_mul_f32_e32 v21, 0xbfb8aa3b, v23
	v_exp_f32_e32 v21, v21
	v_div_fixup_f32 v20, v20, v22, v24
	v_cvt_pk_bf16_f32 v22, v20, s0
	v_add_co_u32_e32 v20, vcc, s2, v64
	v_add_f32_e32 v24, 1.0, v21
	v_div_scale_f32 v25, s[0:1], v24, v24, v23
	v_rcp_f32_e32 v32, v25
	v_addc_co_u32_e32 v21, vcc, 0, v65, vcc
	global_store_short v[20:21], v22, off offset:2048
	v_fma_f32 v22, -v25, v32, 1.0
	v_fmac_f32_e32 v32, v22, v32
	v_div_scale_f32 v22, vcc, v23, v24, v23
	v_mul_f32_e32 v33, v22, v32
	v_fma_f32 v34, -v25, v33, v22
	v_fmac_f32_e32 v33, v34, v32
	v_mul_f32_e32 v34, 0xbfb8aa3b, v26
	v_exp_f32_e32 v34, v34
	v_fma_f32 v22, -v25, v33, v22
	v_div_fmas_f32 v22, v22, v32, v33
	v_div_fixup_f32 v22, v22, v24, v23
	v_add_f32_e32 v25, 1.0, v34
	v_div_scale_f32 v32, s[0:1], v25, v25, v26
	v_rcp_f32_e32 v33, v32
	s_nop 0
	v_cvt_pk_bf16_f32 v22, v22, s0
	global_store_short v[20:21], v22, off offset:2688
	s_mov_b32 s2, 0x8000
	v_fma_f32 v22, -v32, v33, 1.0
	v_fmac_f32_e32 v33, v22, v33
	v_div_scale_f32 v22, vcc, v26, v25, v26
	v_mul_f32_e32 v23, v22, v33
	v_fma_f32 v24, -v32, v23, v22
	v_fmac_f32_e32 v23, v24, v33
	v_add_f32_e32 v24, v27, v69
	v_mul_f32_e32 v27, 0xbfb8aa3b, v24
	v_exp_f32_e32 v27, v27
	v_fma_f32 v22, -v32, v23, v22
	v_div_fmas_f32 v22, v22, v33, v23
	v_div_fixup_f32 v22, v22, v25, v26
	v_add_f32_e32 v23, 1.0, v27
	v_div_scale_f32 v27, s[0:1], v23, v23, v24
	v_rcp_f32_e32 v32, v27
	s_nop 0
	v_cvt_pk_bf16_f32 v22, v22, s0
	global_store_short v[20:21], v22, off offset:3328
	v_fma_f32 v22, -v27, v32, 1.0
	v_fmac_f32_e32 v32, v22, v32
	v_div_scale_f32 v22, vcc, v24, v23, v24
	v_mul_f32_e32 v25, v22, v32
	v_fma_f32 v26, -v27, v25, v22
	v_fmac_f32_e32 v25, v26, v32
	v_add_f32_e32 v26, v28, v69
	v_mul_f32_e32 v28, 0xbfb8aa3b, v26
	v_exp_f32_e32 v28, v28
	v_fma_f32 v22, -v27, v25, v22
	v_div_fmas_f32 v22, v22, v32, v25
	v_div_fixup_f32 v22, v22, v23, v24
	v_add_f32_e32 v25, 1.0, v28
	v_div_scale_f32 v27, s[0:1], v25, v25, v26
	v_rcp_f32_e32 v28, v27
	s_nop 0
	v_cvt_pk_bf16_f32 v22, v22, s0
	global_store_short v[20:21], v22, off offset:3968
	v_fma_f32 v22, -v27, v28, 1.0
	v_fmac_f32_e32 v28, v22, v28
	v_div_scale_f32 v22, vcc, v26, v25, v26
	v_mul_f32_e32 v23, v22, v28
	v_fma_f32 v24, -v27, v23, v22
	v_fmac_f32_e32 v23, v24, v28
	v_fma_f32 v22, -v27, v23, v22
	v_add_f32_e32 v24, v29, v69
	v_div_fmas_f32 v22, v22, v28, v23
	v_mul_f32_e32 v23, 0xbfb8aa3b, v24
	v_exp_f32_e32 v23, v23
	v_div_fixup_f32 v22, v22, v25, v26
	v_cvt_pk_bf16_f32 v25, v22, s0
	v_add_co_u32_e32 v22, vcc, s2, v64
	v_add_f32_e32 v26, 1.0, v23
	v_div_scale_f32 v27, s[0:1], v26, v26, v24
	v_rcp_f32_e32 v28, v27
	v_addc_co_u32_e32 v23, vcc, 0, v65, vcc
	global_store_short v[22:23], v25, off offset:3072
	v_fma_f32 v25, -v27, v28, 1.0
	v_fmac_f32_e32 v28, v25, v28
	v_div_scale_f32 v25, vcc, v24, v26, v24
	v_mul_f32_e32 v29, v25, v28
	v_fma_f32 v32, -v27, v29, v25
	v_fmac_f32_e32 v29, v32, v28
	v_mul_f32_e32 v32, 0xbfb8aa3b, v30
	v_exp_f32_e32 v32, v32
	v_fma_f32 v25, -v27, v29, v25
	v_div_fmas_f32 v25, v25, v28, v29
	v_div_fixup_f32 v24, v25, v26, v24
	v_add_f32_e32 v27, 1.0, v32
	v_div_scale_f32 v28, s[0:1], v27, v27, v30
	v_rcp_f32_e32 v29, v28
	s_nop 0
	v_cvt_pk_bf16_f32 v24, v24, s0
	global_store_short v[22:23], v24, off offset:3712
	s_mov_b32 s2, 0x9000
	v_fma_f32 v24, -v28, v29, 1.0
	v_fmac_f32_e32 v29, v24, v29
	v_div_scale_f32 v24, vcc, v30, v27, v30
	v_mul_f32_e32 v25, v24, v29
	v_fma_f32 v26, -v28, v25, v24
	v_fmac_f32_e32 v25, v26, v29
	v_fma_f32 v24, -v28, v25, v24
	v_add_f32_e32 v26, v31, v69
	v_div_fmas_f32 v24, v24, v29, v25
	v_mul_f32_e32 v25, 0xbfb8aa3b, v26
	v_exp_f32_e32 v25, v25
	v_div_fixup_f32 v24, v24, v27, v30
	v_cvt_pk_bf16_f32 v27, v24, s0
	v_add_co_u32_e32 v24, vcc, s2, v64
	v_add_f32_e32 v28, 1.0, v25
	v_div_scale_f32 v29, s[0:1], v28, v28, v26
	v_rcp_f32_e32 v30, v29
	v_addc_co_u32_e32 v25, vcc, 0, v65, vcc
	global_store_short v[24:25], v27, off offset:256
	v_fma_f32 v27, -v29, v30, 1.0
	v_fmac_f32_e32 v30, v27, v30
	v_div_scale_f32 v27, vcc, v26, v28, v26
	v_mul_f32_e32 v31, v27, v30
	v_fma_f32 v32, -v29, v31, v27
	v_fmac_f32_e32 v31, v32, v30
	v_mul_f32_e32 v32, 0xbfb8aa3b, v0
	v_exp_f32_e32 v32, v32
	v_fma_f32 v27, -v29, v31, v27
	v_div_fmas_f32 v27, v27, v30, v31
	v_div_fixup_f32 v26, v27, v28, v26
	v_add_f32_e32 v29, 1.0, v32
	v_div_scale_f32 v30, s[0:1], v29, v29, v0
	v_rcp_f32_e32 v31, v30
	s_nop 0
	v_cvt_pk_bf16_f32 v26, v26, s0
	global_store_short v[24:25], v26, off offset:896
	v_fma_f32 v26, -v30, v31, 1.0
	v_fmac_f32_e32 v31, v26, v31
	v_div_scale_f32 v26, vcc, v0, v29, v0
	v_mul_f32_e32 v27, v26, v31
	v_fma_f32 v28, -v30, v27, v26
	v_fmac_f32_e32 v27, v28, v31
	v_mul_f32_e32 v28, 0xbfb8aa3b, v1
	v_exp_f32_e32 v28, v28
	v_fma_f32 v26, -v30, v27, v26
	v_div_fmas_f32 v26, v26, v31, v27
	v_div_fixup_f32 v0, v26, v29, v0
	v_add_f32_e32 v27, 1.0, v28
	v_div_scale_f32 v28, s[0:1], v27, v27, v1
	v_rcp_f32_e32 v30, v28
	s_nop 0
	v_cvt_pk_bf16_f32 v0, v0, s0
	global_store_short v[16:17], v0, off offset:64
	v_fma_f32 v0, -v28, v30, 1.0
	v_fmac_f32_e32 v30, v0, v30
	v_div_scale_f32 v0, vcc, v1, v27, v1
	v_mul_f32_e32 v26, v0, v30
	v_fma_f32 v29, -v28, v26, v0
	v_fmac_f32_e32 v26, v29, v30
	v_mul_f32_e32 v29, 0xbfb8aa3b, v2
	v_exp_f32_e32 v29, v29
	v_fma_f32 v0, -v28, v26, v0
	v_div_fmas_f32 v0, v0, v30, v26
	v_div_fixup_f32 v0, v0, v27, v1
	v_add_f32_e32 v26, 1.0, v29
	v_div_scale_f32 v28, s[0:1], v26, v26, v2
	v_rcp_f32_e32 v29, v28
	s_nop 0
	v_cvt_pk_bf16_f32 v0, v0, s0
	global_store_short v[16:17], v0, off offset:704
	v_fma_f32 v0, -v28, v29, 1.0
	v_fmac_f32_e32 v29, v0, v29
	v_div_scale_f32 v0, vcc, v2, v26, v2
	v_mul_f32_e32 v1, v0, v29
	v_fma_f32 v27, -v28, v1, v0
	v_fmac_f32_e32 v1, v27, v29
	v_mul_f32_e32 v27, 0xbfb8aa3b, v3
	v_exp_f32_e32 v27, v27
	v_fma_f32 v0, -v28, v1, v0
	v_div_fmas_f32 v0, v0, v29, v1
	v_div_fixup_f32 v0, v0, v26, v2
	v_add_f32_e32 v1, 1.0, v27
	v_div_scale_f32 v27, s[0:1], v1, v1, v3
	v_rcp_f32_e32 v28, v27
	s_nop 0
	v_cvt_pk_bf16_f32 v0, v0, s0
	global_store_short v[16:17], v0, off offset:1344
	v_fma_f32 v0, -v27, v28, 1.0
	v_fmac_f32_e32 v28, v0, v28
	v_div_scale_f32 v0, vcc, v3, v1, v3
	v_mul_f32_e32 v2, v0, v28
	v_fma_f32 v26, -v27, v2, v0
	v_fmac_f32_e32 v2, v26, v28
	v_mul_f32_e32 v26, 0xbfb8aa3b, v4
	v_exp_f32_e32 v26, v26
	v_fma_f32 v0, -v27, v2, v0
	v_div_fmas_f32 v0, v0, v28, v2
	v_div_fixup_f32 v0, v0, v1, v3
	v_add_f32_e32 v2, 1.0, v26
	v_div_scale_f32 v26, s[0:1], v2, v2, v4
	v_rcp_f32_e32 v27, v26
	s_nop 0
	v_cvt_pk_bf16_f32 v0, v0, s0
	global_store_short v[16:17], v0, off offset:1984
	v_fma_f32 v0, -v26, v27, 1.0
	v_fmac_f32_e32 v27, v0, v27
	v_div_scale_f32 v0, vcc, v4, v2, v4
	v_mul_f32_e32 v1, v0, v27
	v_fma_f32 v3, -v26, v1, v0
	v_fmac_f32_e32 v1, v3, v27
	v_add_f32_e32 v3, v5, v68
	v_mul_f32_e32 v5, 0xbfb8aa3b, v3
	v_exp_f32_e32 v5, v5
	v_fma_f32 v0, -v26, v1, v0
	v_div_fmas_f32 v0, v0, v27, v1
	v_div_fixup_f32 v0, v0, v2, v4
	v_add_f32_e32 v1, 1.0, v5
	v_div_scale_f32 v5, s[0:1], v1, v1, v3
	v_rcp_f32_e32 v16, v5
	s_nop 0
	v_cvt_pk_bf16_f32 v0, v0, s0
	global_store_short v[18:19], v0, off offset:1088
	v_fma_f32 v0, -v5, v16, 1.0
	v_fmac_f32_e32 v16, v0, v16
	v_div_scale_f32 v0, vcc, v3, v1, v3
	v_mul_f32_e32 v2, v0, v16
	v_fma_f32 v4, -v5, v2, v0
	v_fmac_f32_e32 v2, v4, v16
	v_add_f32_e32 v4, v6, v68
	v_mul_f32_e32 v6, 0xbfb8aa3b, v4
	v_exp_f32_e32 v6, v6
	v_fma_f32 v0, -v5, v2, v0
	v_div_fmas_f32 v0, v0, v16, v2
	v_div_fixup_f32 v0, v0, v1, v3
	v_add_f32_e32 v2, 1.0, v6
	v_div_scale_f32 v5, s[0:1], v2, v2, v4
	v_rcp_f32_e32 v6, v5
	s_nop 0
	v_cvt_pk_bf16_f32 v0, v0, s0
	global_store_short v[18:19], v0, off offset:1728
	v_fma_f32 v0, -v5, v6, 1.0
	v_fmac_f32_e32 v6, v0, v6
	v_div_scale_f32 v0, vcc, v4, v2, v4
	v_mul_f32_e32 v1, v0, v6
	v_fma_f32 v3, -v5, v1, v0
	v_fmac_f32_e32 v1, v3, v6
	v_add_f32_e32 v3, v7, v68
	v_mul_f32_e32 v7, 0xbfb8aa3b, v3
	v_exp_f32_e32 v7, v7
	v_fma_f32 v0, -v5, v1, v0
	v_div_fmas_f32 v0, v0, v6, v1
	v_div_fixup_f32 v0, v0, v2, v4
	v_add_f32_e32 v1, 1.0, v7
	v_div_scale_f32 v5, s[0:1], v1, v1, v3
	v_rcp_f32_e32 v6, v5
	s_nop 0
	v_cvt_pk_bf16_f32 v0, v0, s0
	global_store_short v[18:19], v0, off offset:2368
	v_fma_f32 v0, -v5, v6, 1.0
	v_fmac_f32_e32 v6, v0, v6
	v_div_scale_f32 v0, vcc, v3, v1, v3
	v_mul_f32_e32 v2, v0, v6
	v_fma_f32 v4, -v5, v2, v0
	v_fmac_f32_e32 v2, v4, v6
	v_add_f32_e32 v4, v8, v68
	v_mul_f32_e32 v7, 0xbfb8aa3b, v4
	v_exp_f32_e32 v7, v7
	v_fma_f32 v0, -v5, v2, v0
	v_div_fmas_f32 v0, v0, v6, v2
	v_div_fixup_f32 v0, v0, v1, v3
	v_add_f32_e32 v2, 1.0, v7
	v_div_scale_f32 v5, s[0:1], v2, v2, v4
	v_rcp_f32_e32 v6, v5
	s_nop 0
	v_cvt_pk_bf16_f32 v0, v0, s0
	global_store_short v[18:19], v0, off offset:3008
	v_fma_f32 v0, -v5, v6, 1.0
	v_fmac_f32_e32 v6, v0, v6
	v_div_scale_f32 v0, vcc, v4, v2, v4
	v_mul_f32_e32 v1, v0, v6
	v_fma_f32 v3, -v5, v1, v0
	v_fmac_f32_e32 v1, v3, v6
	v_add_f32_e32 v3, v9, v68
	v_mul_f32_e32 v7, 0xbfb8aa3b, v3
	v_exp_f32_e32 v7, v7
	v_fma_f32 v0, -v5, v1, v0
	v_div_fmas_f32 v0, v0, v6, v1
	v_div_fixup_f32 v0, v0, v2, v4
	v_add_f32_e32 v1, 1.0, v7
	v_div_scale_f32 v5, s[0:1], v1, v1, v3
	v_rcp_f32_e32 v6, v5
	s_nop 0
	v_cvt_pk_bf16_f32 v0, v0, s0
	global_store_short v[20:21], v0, off offset:2112
	v_fma_f32 v0, -v5, v6, 1.0
	v_fmac_f32_e32 v6, v0, v6
	v_div_scale_f32 v0, vcc, v3, v1, v3
	v_mul_f32_e32 v2, v0, v6
	v_fma_f32 v4, -v5, v2, v0
	v_fmac_f32_e32 v2, v4, v6
	v_add_f32_e32 v4, v10, v68
	v_mul_f32_e32 v7, 0xbfb8aa3b, v4
	v_exp_f32_e32 v7, v7
	v_fma_f32 v0, -v5, v2, v0
	v_div_fmas_f32 v0, v0, v6, v2
	v_div_fixup_f32 v0, v0, v1, v3
	v_add_f32_e32 v2, 1.0, v7
	v_div_scale_f32 v5, s[0:1], v2, v2, v4
	v_rcp_f32_e32 v6, v5
	s_nop 0
	v_cvt_pk_bf16_f32 v0, v0, s0
	global_store_short v[20:21], v0, off offset:2752
	v_fma_f32 v0, -v5, v6, 1.0
	v_fmac_f32_e32 v6, v0, v6
	v_div_scale_f32 v0, vcc, v4, v2, v4
	v_mul_f32_e32 v1, v0, v6
	v_fma_f32 v3, -v5, v1, v0
	v_fmac_f32_e32 v1, v3, v6
	v_add_f32_e32 v3, v11, v68
	v_mul_f32_e32 v7, 0xbfb8aa3b, v3
	v_exp_f32_e32 v7, v7
	v_fma_f32 v0, -v5, v1, v0
	v_div_fmas_f32 v0, v0, v6, v1
	v_div_fixup_f32 v0, v0, v2, v4
	v_add_f32_e32 v1, 1.0, v7
	v_div_scale_f32 v5, s[0:1], v1, v1, v3
	v_rcp_f32_e32 v6, v5
	s_nop 0
	v_cvt_pk_bf16_f32 v0, v0, s0
	global_store_short v[20:21], v0, off offset:3392
	v_fma_f32 v0, -v5, v6, 1.0
	v_fmac_f32_e32 v6, v0, v6
	v_div_scale_f32 v0, vcc, v3, v1, v3
	v_mul_f32_e32 v2, v0, v6
	v_fma_f32 v4, -v5, v2, v0
	v_fmac_f32_e32 v2, v4, v6
	v_add_f32_e32 v4, v12, v68
	v_mul_f32_e32 v7, 0xbfb8aa3b, v4
	v_exp_f32_e32 v7, v7
	v_fma_f32 v0, -v5, v2, v0
	v_div_fmas_f32 v0, v0, v6, v2
	v_div_fixup_f32 v0, v0, v1, v3
	v_add_f32_e32 v2, 1.0, v7
	v_div_scale_f32 v5, s[0:1], v2, v2, v4
	v_rcp_f32_e32 v6, v5
	s_nop 0
	v_cvt_pk_bf16_f32 v0, v0, s0
	global_store_short v[20:21], v0, off offset:4032
	v_fma_f32 v0, -v5, v6, 1.0
	v_fmac_f32_e32 v6, v0, v6
	v_div_scale_f32 v0, vcc, v4, v2, v4
	v_mul_f32_e32 v1, v0, v6
	v_fma_f32 v3, -v5, v1, v0
	v_fmac_f32_e32 v1, v3, v6
	v_add_f32_e32 v3, v13, v68
	v_mul_f32_e32 v7, 0xbfb8aa3b, v3
	v_exp_f32_e32 v7, v7
	v_fma_f32 v0, -v5, v1, v0
	v_div_fmas_f32 v0, v0, v6, v1
	v_div_fixup_f32 v0, v0, v2, v4
	v_add_f32_e32 v1, 1.0, v7
	v_div_scale_f32 v5, s[0:1], v1, v1, v3
	v_rcp_f32_e32 v6, v5
	s_nop 0
	v_cvt_pk_bf16_f32 v0, v0, s0
	global_store_short v[22:23], v0, off offset:3136
	v_fma_f32 v0, -v5, v6, 1.0
	v_fmac_f32_e32 v6, v0, v6
	v_div_scale_f32 v0, vcc, v3, v1, v3
	v_mul_f32_e32 v2, v0, v6
	v_fma_f32 v4, -v5, v2, v0
	v_fmac_f32_e32 v2, v4, v6
	v_add_f32_e32 v4, v14, v68
	v_mul_f32_e32 v7, 0xbfb8aa3b, v4
	v_exp_f32_e32 v7, v7
	v_fma_f32 v0, -v5, v2, v0
	v_div_fmas_f32 v0, v0, v6, v2
	v_div_fixup_f32 v0, v0, v1, v3
	v_add_f32_e32 v2, 1.0, v7
	v_div_scale_f32 v5, s[0:1], v2, v2, v4
	v_rcp_f32_e32 v6, v5
	s_nop 0
	v_cvt_pk_bf16_f32 v0, v0, s0
	global_store_short v[22:23], v0, off offset:3776
	v_fma_f32 v0, -v5, v6, 1.0
	v_fmac_f32_e32 v6, v0, v6
	v_div_scale_f32 v0, vcc, v4, v2, v4
	v_mul_f32_e32 v1, v0, v6
	v_fma_f32 v3, -v5, v1, v0
	v_fmac_f32_e32 v1, v3, v6
	v_add_f32_e32 v3, v15, v68
	v_mul_f32_e32 v7, 0xbfb8aa3b, v3
	v_exp_f32_e32 v7, v7
	v_fma_f32 v0, -v5, v1, v0
	v_div_fmas_f32 v0, v0, v6, v1
	v_div_fixup_f32 v0, v0, v2, v4
	v_add_f32_e32 v1, 1.0, v7
	v_div_scale_f32 v5, s[0:1], v1, v1, v3
	v_rcp_f32_e32 v6, v5
	s_nop 0
	v_cvt_pk_bf16_f32 v0, v0, s0
	global_store_short v[24:25], v0, off offset:320
	v_fma_f32 v0, -v5, v6, 1.0
	v_fmac_f32_e32 v6, v0, v6
	v_div_scale_f32 v0, vcc, v3, v1, v3
	v_mul_f32_e32 v2, v0, v6
	v_fma_f32 v4, -v5, v2, v0
	v_fmac_f32_e32 v2, v4, v6
	v_fma_f32 v0, -v5, v2, v0
	v_div_fmas_f32 v0, v0, v6, v2
	v_div_fixup_f32 v0, v0, v1, v3
	v_cvt_pk_bf16_f32 v0, v0, s0
	global_store_short v[24:25], v0, off offset:960
	s_waitcnt lgkmcnt(0)
	s_barrier
	s_waitcnt vmcnt(0)
	s_barrier
	s_mov_b64 s[4:5], exec
	v_readlane_b32 s0, v254, 29
	v_readlane_b32 s1, v254, 30
	s_and_b64 s[0:1], s[4:5], s[0:1]
	s_mov_b64 exec, s[0:1]
	s_cbranch_execz .Lc2_pub_done
	buffer_wbl2 sc1
	s_waitcnt vmcnt(0)
	v_mov_b32_e32 v0, 0
	v_mov_b32_e32 v1, 1
	global_atomic_add v0, v1, s[68:69] offset:160
.Lc2_pub_done:
	s_mov_b64 exec, s[4:5]
	v_readlane_b32 s2, v255, 12
	s_bitcmp1_b32 s2, 0
	s_cbranch_scc1 .LBB0_562
	s_and_b64 s[0:1], s[4:5], s[0:1]
	s_mov_b64 exec, s[0:1]
	s_cbranch_execz .Lc2_wait_done
	v_mov_b32_e32 v0, 0
.Lc2_spin:
	global_load_dword v1, v0, s[68:69] offset:160 sc1
	s_waitcnt vmcnt(0)
	v_cmp_gt_u32_e32 vcc, 64, v1
	s_cbranch_vccz .Lc2_spun
	s_sleep 2
	s_branch .Lc2_spin

.Lc2_wait_done:
	s_mov_b64 exec, s[4:5]
	s_barrier
	v_readlane_b32 s2, v255, 12
	s_lshr_b32 s4, s2, 1
	s_and_b32 s4, s4, 15
	s_lshr_b32 s0, s2, 5
	s_lshl_b32 s0, s0, 4
	s_or_b32 s4, s4, s0
	s_or_b32 s4, s4, 0x100
	s_mov_b64 s[6:7], -1
	s_branch .Lcmp2_entry

.LBB0_899:
	v_readlane_b32 s4, v255, 12
	s_and_b32 s0, s4, 0xffffffe0
	s_cmpk_lg_i32 s0, 0x100
	s_cselect_b64 s[0:1], -1, 0
	s_xor_b64 s[2:3], s[12:13], -1
	s_or_b64 s[0:1], s[0:1], s[2:3]
	s_mov_b64 s[6:7], -1
	s_and_b64 vcc, exec, s[0:1]
	s_branch .LBB0_1153
.Lcmp2_entry:
	s_lshl_b32 s0, s4, 7
	v_readlane_b32 s16, v255, 61
	s_and_b32 s0, s0, 0x780
	s_and_b32 s1, s4, 0x110
	v_readlane_b32 s20, v254, 1
	v_readlane_b32 s21, v254, 2
	v_lshlrev_b32_e32 v0, 5, v167
	s_cmpk_lg_i32 s1, 0x100
	v_readlane_b32 s22, v254, 3
	v_readlane_b32 s23, v254, 4
	s_mov_b64 s[8:9], s[20:21]
	v_add_u32_e32 v1, s0, v0
	v_or_b32_e32 v0, v0, v177
	s_cselect_b64 s[14:15], -1, 0
	s_cmpk_eq_i32 s1, 0x100
	s_mov_b64 s[10:11], s[22:23]
	v_lshlrev_b32_e32 v5, 3, v179
	v_mul_u32_u24_e32 v0, 0x140, v0
	v_readlane_b32 s17, v255, 62
	v_readlane_b32 s18, v255, 63
	v_readlane_b32 s19, v254, 0
	v_readlane_b32 s24, v254, 5
	v_readlane_b32 s25, v254, 6
	v_readlane_b32 s26, v254, 7
	v_readlane_b32 s27, v254, 8
	v_readlane_b32 s28, v254, 9
	v_readlane_b32 s29, v254, 10
	v_readlane_b32 s30, v254, 11
	v_readlane_b32 s31, v254, 12
	s_cselect_b32 s1, s9, s11
	v_or_b32_e32 v4, v0, v5
	v_lshlrev_b32_e32 v0, 6, v166
	v_mov_b32_e32 v3, s1
	v_readlane_b32 s16, v254, 13
	v_or_b32_e32 v1, v1, v177
	v_and_b32_e32 v0, 0x7c0, v0
	v_bitop3_b32 v7, v175, v148, 3 bitop3:0x78
	s_movk_i32 s1, 0x2000
	v_readlane_b32 s28, v254, 25
	v_readlane_b32 s29, v254, 26
	v_readlane_b32 s30, v254, 27
	v_readlane_b32 s31, v254, 28
	v_mul_u32_u24_e32 v1, 0x140, v1
	v_lshl_or_b32 v6, v172, 12, v0
	v_lshlrev_b32_e32 v7, 4, v7
	v_lshlrev_b32_e32 v8, 4, v178
	v_or3_b32 v0, v176, v0, s1
	s_cselect_b32 s5, s29, s31
	s_cselect_b32 s4, s28, s30
	v_or_b32_e32 v164, v0, v7
	v_or_b32_e32 v165, v0, v8
	v_or_b32_e32 v0, v1, v5
	v_mov_b32_e32 v1, 0
	v_readfirstlane_b32 s1, v149
	v_or_b32_e32 v5, 0x400, v149
	s_cselect_b32 s2, s8, s10
	v_or_b32_e32 v162, v6, v7
	v_or_b32_e32 v163, v6, v8
	s_waitcnt vmcnt(0)
	v_lshl_add_u64 v[6:7], v[0:1], 1, s[4:5]
	s_mov_b32 m0, s1
	v_add_u32_e32 v8, 0x1400, v0
	v_mov_b32_e32 v9, v1
	v_readfirstlane_b32 s1, v5
	v_add_u32_e32 v175, 0x2000, v149
	v_mov_b32_e32 v2, s2
	global_load_lds_dwordx4 v[6:7], off
	v_lshl_add_u64 v[8:9], v[8:9], 1, s[4:5]
	s_mov_b32 m0, s1
	v_mov_b32_e32 v5, v1
	v_readfirstlane_b32 s1, v175
	v_add_u32_e32 v176, 0x2400, v149
	global_load_lds_dwordx4 v[8:9], off
	v_lshl_add_u64 v[2:3], v[4:5], 1, v[2:3]
	s_mov_b32 m0, s1
	s_mov_b64 s[2:3], 0x2800
	v_readfirstlane_b32 s1, v176
	v_add_u32_e32 v177, 0x4000, v149
	global_load_lds_dwordx4 v[2:3], off
	v_lshl_add_u64 v[4:5], v[2:3], 0, s[2:3]
	s_mov_b32 m0, s1
	v_readfirstlane_b32 s1, v177
	global_load_lds_dwordx4 v[4:5], off
	v_lshl_add_u64 v[4:5], v[6:7], 0, 64
	s_mov_b32 m0, s1
	v_add_u32_e32 v178, 0x4400, v149
	global_load_lds_dwordx4 v[4:5], off
	v_add_u32_e32 v4, 0x1420, v0
	v_mov_b32_e32 v5, v1
	v_readfirstlane_b32 s1, v178
	v_add_u32_e32 v179, 0x6000, v149
	v_lshl_add_u64 v[4:5], v[4:5], 1, s[4:5]
	s_mov_b32 m0, s1
	v_readfirstlane_b32 s1, v179
	v_add_u32_e32 v180, 0x6400, v149
	global_load_lds_dwordx4 v[4:5], off
	v_lshl_add_u64 v[4:5], v[2:3], 0, 64
	s_mov_b32 m0, s1
	s_mov_b64 s[2:3], 0x2840
	v_readfirstlane_b32 s1, v180
	v_add_u32_e32 v181, 0x8000, v149
	global_load_lds_dwordx4 v[4:5], off
	v_lshl_add_u64 v[4:5], v[2:3], 0, s[2:3]
	s_mov_b32 m0, s1
	s_mov_b64 s[2:3], 0x80
	v_readfirstlane_b32 s1, v181
	global_load_lds_dwordx4 v[4:5], off
	v_lshl_add_u64 v[4:5], v[6:7], 0, s[2:3]
	s_mov_b32 m0, s1
	v_add_u32_e32 v182, 0x8400, v149
	global_load_lds_dwordx4 v[4:5], off
	v_add_u32_e32 v4, 0x1440, v0
	v_mov_b32_e32 v5, v1
	v_readfirstlane_b32 s1, v182
	v_add_u32_e32 v183, 0xa000, v149
	v_lshl_add_u64 v[4:5], v[4:5], 1, s[4:5]
	s_mov_b32 m0, s1
	v_readfirstlane_b32 s1, v183
	v_add_u32_e32 v184, 0xa400, v149
	global_load_lds_dwordx4 v[4:5], off
	v_lshl_add_u64 v[4:5], v[2:3], 0, s[2:3]
	s_mov_b32 m0, s1
	s_mov_b64 s[2:3], 0x2880
	v_readfirstlane_b32 s1, v184
	global_load_lds_dwordx4 v[4:5], off
	v_lshl_add_u64 v[4:5], v[2:3], 0, s[2:3]
	s_mov_b32 m0, s1
	v_add_u32_e32 v185, 0xc000, v149
	global_load_lds_dwordx4 v[4:5], off
	s_mov_b64 s[2:3], 0xc0
	v_readfirstlane_b32 s1, v185
	s_waitcnt vmcnt(8)
	v_lshl_add_u64 v[4:5], v[6:7], 0, s[2:3]
	s_mov_b32 m0, s1
	v_add_u32_e32 v186, 0xc400, v149
	s_waitcnt lgkmcnt(0)
	s_barrier
	global_load_lds_dwordx4 v[4:5], off
	v_add_u32_e32 v4, 0x1460, v0
	v_mov_b32_e32 v5, v1
	v_readfirstlane_b32 s1, v186
	v_add_u32_e32 v187, 0xe000, v149
	v_lshl_add_u64 v[4:5], v[4:5], 1, s[4:5]
	s_mov_b32 m0, s1
	v_readfirstlane_b32 s1, v187
	v_add_u32_e32 v188, 0xe400, v149
	global_load_lds_dwordx4 v[4:5], off
	v_lshl_add_u64 v[4:5], v[2:3], 0, s[2:3]
	s_mov_b32 m0, s1
	s_mov_b64 s[2:3], 0x28c0
	v_readfirstlane_b32 s1, v188
	global_load_lds_dwordx4 v[4:5], off
	v_lshl_add_u64 v[4:5], v[2:3], 0, s[2:3]
	s_mov_b32 m0, s1
	s_mov_b64 s[2:3], 0x100
	global_load_lds_dwordx4 v[4:5], off
	v_lshl_add_u64 v[128:129], v[6:7], 0, s[2:3]
	v_lshl_add_u64 v[132:133], v[2:3], 0, s[2:3]
	s_mov_b64 s[2:3], 0x2900
	v_lshl_add_u64 v[134:135], v[2:3], 0, s[2:3]
	s_mov_b64 s[2:3], 0x140
	v_lshl_add_u64 v[136:137], v[6:7], 0, s[2:3]
	v_lshl_add_u64 v[140:141], v[2:3], 0, s[2:3]
	s_mov_b64 s[2:3], 0x2940
	v_lshl_add_u64 v[142:143], v[2:3], 0, s[2:3]
	s_mov_b64 s[2:3], 0x180
	v_add_u32_e32 v4, 0x1480, v0
	v_mov_b32_e32 v5, v1
	v_lshl_add_u64 v[144:145], v[6:7], 0, s[2:3]
	v_lshl_add_u64 v[150:151], v[2:3], 0, s[2:3]
	s_mov_b64 s[2:3], 0x2980
	v_lshl_add_u64 v[130:131], v[4:5], 1, s[4:5]
	v_add_u32_e32 v4, 0x14a0, v0
	v_lshl_add_u64 v[152:153], v[2:3], 0, s[2:3]
	s_mov_b64 s[2:3], 0x1c0
	v_lshl_add_u64 v[138:139], v[4:5], 1, s[4:5]
	v_add_u32_e32 v4, 0x14c0, v0
	v_lshl_add_u64 v[154:155], v[6:7], 0, s[2:3]
	v_add_u32_e32 v0, 0x14e0, v0
	v_lshl_add_u64 v[158:159], v[2:3], 0, s[2:3]
	s_mov_b64 s[2:3], 0x29c0
	v_lshl_add_u64 v[146:147], v[4:5], 1, s[4:5]
	v_lshl_add_u64 v[156:157], v[0:1], 1, s[4:5]
	v_lshl_add_u64 v[160:161], v[2:3], 0, s[2:3]
	v_add_u32_e32 v189, 0x400, v149
	v_mov_b32_e32 v0, v1
	v_mov_b32_e32 v2, v1
	v_mov_b32_e32 v3, v1
	v_mov_b32_e32 v4, v1
	v_mov_b32_e32 v6, v1
	v_mov_b32_e32 v7, v1
	v_mov_b32_e32 v8, v1
	v_mov_b32_e32 v9, v1
	v_mov_b32_e32 v10, v1
	v_mov_b32_e32 v11, v1
	v_mov_b32_e32 v12, v1
	v_mov_b32_e32 v13, v1
	v_mov_b32_e32 v14, v1
	v_mov_b32_e32 v15, v1
	v_mov_b32_e32 v16, v1
	v_mov_b32_e32 v17, v1
	v_mov_b32_e32 v18, v1
	v_mov_b32_e32 v19, v1
	v_mov_b32_e32 v20, v1
	v_mov_b32_e32 v21, v1
	v_mov_b32_e32 v22, v1
	v_mov_b32_e32 v23, v1
	v_mov_b32_e32 v24, v1
	v_mov_b32_e32 v25, v1
	v_mov_b32_e32 v26, v1
	v_mov_b32_e32 v27, v1
	v_mov_b32_e32 v28, v1
	v_mov_b32_e32 v29, v1
	v_mov_b32_e32 v30, v1
	v_mov_b32_e32 v31, v1
	v_mov_b32_e32 v32, v1
	v_mov_b32_e32 v33, v1
	v_mov_b32_e32 v34, v1
	v_mov_b32_e32 v35, v1
	v_mov_b32_e32 v36, v1
	v_mov_b32_e32 v37, v1
	v_mov_b32_e32 v38, v1
	v_mov_b32_e32 v39, v1
	v_mov_b32_e32 v40, v1
	v_mov_b32_e32 v41, v1
	v_mov_b32_e32 v42, v1
	v_mov_b32_e32 v43, v1
	v_mov_b32_e32 v44, v1
	v_mov_b32_e32 v45, v1
	v_mov_b32_e32 v46, v1
	v_mov_b32_e32 v47, v1
	v_mov_b32_e32 v48, v1
	v_mov_b32_e32 v49, v1
	v_mov_b32_e32 v50, v1
	v_mov_b32_e32 v51, v1
	v_mov_b32_e32 v52, v1
	v_mov_b32_e32 v53, v1
	v_mov_b32_e32 v54, v1
	v_mov_b32_e32 v55, v1
	v_mov_b32_e32 v56, v1
	v_mov_b32_e32 v57, v1
	v_mov_b32_e32 v58, v1
	v_mov_b32_e32 v59, v1
	v_mov_b32_e32 v60, v1
	v_mov_b32_e32 v61, v1
	v_mov_b32_e32 v62, v1
	v_mov_b32_e32 v63, v1
	v_readlane_b32 s17, v254, 14
	v_readlane_b32 s18, v254, 15
	v_readlane_b32 s19, v254, 16
	v_readlane_b32 s20, v254, 17
	v_readlane_b32 s21, v254, 18
	v_readlane_b32 s22, v254, 19
	v_readlane_b32 s23, v254, 20
	v_readlane_b32 s24, v254, 21
	v_readlane_b32 s25, v254, 22
	v_readlane_b32 s26, v254, 23
	v_readlane_b32 s27, v254, 24
	ds_read_b128 v[64:67], v162 offset:0
	ds_read_b128 v[68:71], v162 offset:0x800
	ds_read_b128 v[76:79], v164 offset:0
	ds_read_b128 v[80:83], v164 offset:0x800
	ds_read_b128 v[84:87], v163 offset:0
	ds_read_b128 v[72:75], v163 offset:0x800
	ds_read_b128 v[92:95], v165 offset:0
	ds_read_b128 v[88:91], v165 offset:0x800
	s_branch .LBB0_902

.LBB0_1149:
	s_or_b64 exec, exec, s[10:11]
	s_waitcnt lgkmcnt(0)
	s_branch .LBB0_562

.LBB0_1208:
	v_writelane_b32 v254, s97, 47
	s_and_b64 vcc, exec, s[12:13]
	s_branch .LBB0_1214
